# ffn_in / a_in tile order: rounds walk the four row-panel groups first, the column block changes every four rounds
# baseline (speedup 1.0000x reference)
.LBB0_72:
	s_add_i32 s59, s59, 1
	s_mul_i32 s4, s59, s62
	s_mul_hi_u32 s5, s59, s63
	s_add_i32 s5, s5, s4
	s_mul_i32 s4, s59, s63
	s_add_u32 s28, s4, s2
	s_addc_u32 s29, s5, s53
	v_cmp_gt_i64_e32 vcc, s[28:29], v[142:143]
	v_cmp_lt_i64_e64 s[4:5], s[28:29], v[140:141]
	s_cbranch_vccnz .LBB0_74
	s_cmp_eq_u32 s42, 0x100
	s_cbranch_scc0 .Lwgm_orig_0
	s_and_b32 s98, s2, 7
	s_lshr_b32 s99, s2, 3
	s_cmp_lt_u32 s59, 8
	s_cbranch_scc0 .Lwgm_tail_0
	s_and_b32 s100, s59, 3
	s_lshl_b32 s100, s100, 2
	s_and_b32 s101, s99, 3
	s_add_i32 s26, s100, s101
	s_lshr_b32 s100, s59, 2
	s_lshl_b32 s100, s100, 3
	s_lshr_b32 s101, s99, 2
	s_add_i32 s22, s100, s101
	s_branch .Lwgm_join_0

.LBB0_248:
	s_add_i32 s90, s90, 1
	s_mul_i32 s3, s90, s80
	s_mul_hi_u32 s12, s90, s81
	s_add_i32 s12, s12, s3
	s_mul_i32 s3, s90, s81
	s_add_u32 s62, s3, s2
	s_addc_u32 s63, s12, s82
	v_cmp_gt_i64_e32 vcc, s[62:63], v[174:175]
	v_cmp_lt_i64_e64 s[12:13], s[62:63], v[172:173]
	s_cbranch_vccnz .LBB0_254
	s_cmp_eq_u32 s42, 0x100
	s_cbranch_scc0 .Lwgm_orig_1
	s_and_b32 s98, s2, 7
	s_lshr_b32 s99, s2, 3
	s_and_b32 s100, s90, 3
	s_lshl_b32 s100, s100, 2
	s_and_b32 s101, s99, 3
	s_add_i32 s60, s100, s101
	s_lshr_b32 s100, s90, 2
	s_lshl_b32 s100, s100, 3
	s_lshr_b32 s101, s99, 2
	s_add_i32 s58, s100, s101
	s_lshl_b32 s98, s98, 4
	s_add_i32 s60, s60, s98
	s_branch .LBB0_254

.LBB0_523:
	s_add_i32 s61, s61, 1
	s_mul_i32 s10, s61, s64
	s_mul_hi_u32 s11, s61, s65
	s_add_i32 s11, s11, s10
	s_mul_i32 s10, s61, s65
	s_add_u32 s30, s10, s2
	s_addc_u32 s31, s11, s55
	v_cmp_gt_i64_e32 vcc, s[30:31], v[142:143]
	v_cmp_lt_i64_e64 s[10:11], s[30:31], v[140:141]
	s_cbranch_vccnz .LBB0_525
	s_cmp_eq_u32 s42, 0x100
	s_cbranch_scc0 .Lwgm_orig_2
	s_and_b32 s98, s2, 7
	s_lshr_b32 s99, s2, 3
	s_cmp_lt_u32 s61, 8
	s_cbranch_scc0 .Lwgm_tail_2
	s_and_b32 s100, s61, 3
	s_lshl_b32 s100, s100, 2
	s_and_b32 s101, s99, 3
	s_add_i32 s28, s100, s101
	s_lshr_b32 s100, s61, 2
	s_lshl_b32 s100, s100, 3
	s_lshr_b32 s101, s99, 2
	s_add_i32 s26, s100, s101
	s_branch .Lwgm_join_2

.LBB0_1094:
	s_add_i32 s56, s56, 1
	s_mul_i32 s6, s56, s59
	s_mul_hi_u32 s7, s56, s60
	s_add_i32 s7, s7, s6
	s_mul_i32 s6, s56, s60
	s_add_u32 s26, s6, s2
	s_addc_u32 s27, s7, s50
	v_cmp_gt_i64_e32 vcc, s[26:27], v[142:143]
	v_cmp_lt_i64_e64 s[6:7], s[26:27], v[140:141]
	s_cbranch_vccnz .LBB0_1096
	s_cmp_eq_u32 s42, 0x100
	s_cbranch_scc0 .Lwgm_orig_4
	s_and_b32 s98, s2, 7
	s_lshr_b32 s99, s2, 3
	s_cmp_lt_u32 s56, 8
	s_cbranch_scc0 .Lwgm_tail_4
	s_and_b32 s100, s56, 3
	s_lshl_b32 s100, s100, 2
	s_and_b32 s101, s99, 3
	s_add_i32 s24, s100, s101
	s_lshr_b32 s100, s56, 2
	s_lshl_b32 s100, s100, 3
	s_lshr_b32 s101, s99, 2
	s_add_i32 s22, s100, s101
	s_branch .Lwgm_join_4
